# K/V tile loads of the pipelined A loop use an SGPR base with a 32-bit per-lane offset (base advanced on the scalar unit) instead of 64-bit VGPR pointers
# speedup vs baseline: 1.0361x; 1.0044x over previous
; #define LAS __attribute__((address_space(3)))
; __device__ __forceinline__ unsigned pk2(float lo, float hi) { f32x2_t v = {lo, hi}; bf16x2_t b = __builtin_convertvector(v, bf16x2_t); return __builtin_bit_cast(unsigned, b); }
; template <bool TRACK> ...
;     ...
;     { const int qrow = wave * 32 + r32; const bf16* qp = Qraw + (size_t)qrow * INW + hi * 8;
;       float qv[4][8]; float ss = 0.f;
; #pragma unroll
;       for (int d = 0; d < 4; ++d) { unpack8(*(const u32x4*)(qp + d * 16), qv[d]);
; #pragma unroll
;           for (int e = 0; e < 8; ++e) ss += qv[d][e] * qv[d][e]; }
;       ss += __shfl_xor(ss, 32);
;       const float rs = rsqrtf(ss * (1.0f / 64.0f) + 1e-6f) * (0.125f * LOG2E);
; #pragma unroll
;       for (int d = 0; d < 4; ++d) { const f32x4 w0 = *(const f32x4*)(qnw + d * 16 + hi * 8), w1 = *(const f32x4*)(qnw + d * 16 + hi * 8 + 4);
;           qv[d][0] *= rs * w0.x; qv[d][1] *= rs * w0.y; qv[d][2] *= rs * w0.z; qv[d][3] *= rs * w0.w; qv[d][4] *= rs * w1.x; qv[d][5] *= rs * w1.y; qv[d][6] *= rs * w1.z; qv[d][7] *= rs * w1.w; }
;       if (tpos0 >= 0) { const float* cp = ropet + (size_t)(tpos0 + qrow) * 32 + hi * 8; const float* sp = cp + 2048 * 32;
; #pragma unroll
;           for (int ax = 0; ax < 2; ++ax) { const f32x4 c0 = *(const f32x4*)(cp + ax * 16), c1 = *(const f32x4*)(cp + ax * 16 + 4), s0_ = *(const f32x4*)(sp + ax * 16), s1_ = *(const f32x4*)(sp + ax * 16 + 4);
;               const float cc[8] = {c0.x, c0.y, c0.z, c0.w, c1.x, c1.y, c1.z, c1.w}, sn[8] = {s0_.x, s0_.y, s0_.z, s0_.w, s1_.x, s1_.y, s1_.z, s1_.w};
; #pragma unroll
;               for (int e = 0; e < 8; ++e) { const float xa = qv[2 * ax][e], xb = qv[2 * ax + 1][e]; qv[2 * ax][e] = xa * cc[e] - xb * sn[e]; qv[2 * ax + 1][e] = xb * cc[e] + xa * sn[e]; } } }
; #pragma unroll
;       for (int d = 0; d < 4; ++d) { u32x4 w; w.x = pk2(qv[d][0], qv[d][1]); w.y = pk2(qv[d][2], qv[d][3]); w.z = pk2(qv[d][4], qv[d][5]); w.w = pk2(qv[d][6], qv[d][7]); qf[d] = __builtin_bit_cast(bf16x8, w); } }
;     __syncthreads();
;     *(LAS u32x4*)(lds + (srow * 72 + sc * 8) * 2) = kreg; { LAS u32x2* vw_ = (LAS u32x2*)(lds + 9216 + (srow * 68 + sc * 8) * 2); vw_[0] = (u32x2){vreg.x, vreg.y}; vw_[1] = (u32x2){vreg.z, vreg.w}; }
.LBB0_165:
	s_andn2_saveexec_b64 s[48:49], s[48:49]
	s_cbranch_execz .LBB0_169
	ds_bpermute_b32 v19, v188, v18
	s_mov_b32 s4, 0x800000
	s_add_i32 s51, s51, s73
	s_and_b32 s20, s51, 0x1fff
	s_mul_i32 s22, s20, 0x48000
	s_waitcnt lgkmcnt(0)
	v_add_f32_e32 v18, v18, v19
	v_fmamk_f32 v18, v18, 0x3c800000, v163
	v_cmp_gt_f32_e32 vcc, s4, v18
	v_mul_f32_e32 v19, 0x4b800000, v18
	s_add_u32 s20, s50, s22
	v_cndmask_b32_e32 v18, v18, v19, vcc
	v_rsq_f32_e32 v18, v18
	s_addc_u32 s21, 0, 0
	v_mov_b32_e32 v135, v1
	v_readlane_b32 s4, v250, 63
	v_mul_f32_e32 v19, 0x45800000, v18
	v_cndmask_b32_e32 v18, v18, v19, vcc
	v_mul_f32_e32 v70, 0x3e38aa3b, v18
	global_load_dwordx4 v[26:29], v[16:17], off offset:192
	global_load_dwordx4 v[18:21], v[16:17], off offset:144
	global_load_dwordx4 v[30:33], v[16:17], off offset:128
	global_load_dwordx4 v[72:75], v[16:17], off offset:16
	global_load_dwordx4 v[76:79], v[16:17], off
	global_load_dwordx4 v[80:83], v[16:17], off offset:80
	global_load_dwordx4 v[84:87], v[16:17], off offset:64
	global_load_dwordx4 v[88:91], v[22:23], off offset:16
	global_load_dwordx4 v[92:95], v[22:23], off
	global_load_dwordx4 v[96:99], v[14:15], off offset:16
	s_nop 0
	global_load_dwordx4 v[14:17], v[14:15], off
	s_waitcnt vmcnt(11)
	v_pk_mul_f32 v[10:11], v[10:11], v[70:71] op_sel_hi:[1,0]
	v_pk_mul_f32 v[12:13], v[12:13], v[70:71] op_sel_hi:[1,0]
	v_pk_mul_f32 v[40:41], v[10:11], v[40:41]
	v_pk_mul_f32 v[12:13], v[12:13], v[36:37]
	v_readlane_b32 s5, v249, 0
	s_waitcnt vmcnt(10)
	v_pk_mul_f32 v[26:27], v[26:27], v[70:71] op_sel_hi:[1,0]
	s_waitcnt vmcnt(9)
	v_pk_mul_f32 v[10:11], v[18:19], v[70:71] op_sel_hi:[1,0]
	v_pk_mul_f32 v[28:29], v[28:29], v[70:71] op_sel_hi:[1,0]
	v_pk_mul_f32 v[18:19], v[10:11], v[38:39]
	s_waitcnt vmcnt(6)
	v_pk_mul_f32 v[68:69], v[76:77], v[70:71] op_sel_hi:[1,0]
	s_nop 0
	v_pk_mul_f32 v[66:67], v[68:69], v[66:67]
	s_waitcnt vmcnt(4)
	v_pk_mul_f32 v[68:69], v[84:85], v[70:71] op_sel_hi:[1,0]
	s_nop 0
	v_pk_mul_f32 v[68:69], v[68:69], v[64:65]
	s_waitcnt vmcnt(0)
	v_pk_mul_f32 v[64:65], v[14:15], v[68:69]
	v_pk_mul_f32 v[14:15], v[14:15], v[66:67]
	v_pk_fma_f32 v[64:65], v[92:93], v[66:67], v[64:65] neg_lo:[0,0,1] neg_hi:[0,0,1]
	v_pk_fma_f32 v[66:67], v[92:93], v[68:69], v[14:15]
	v_pk_mul_f32 v[14:15], v[78:79], v[70:71] op_sel_hi:[1,0]
	s_nop 0
	v_pk_mul_f32 v[14:15], v[14:15], v[62:63]
	v_pk_mul_f32 v[62:63], v[86:87], v[70:71] op_sel_hi:[1,0]
	s_nop 0
	v_pk_mul_f32 v[62:63], v[62:63], v[60:61]
	s_nop 0
	v_pk_mul_f32 v[60:61], v[16:17], v[62:63]
	s_nop 0
	v_pk_fma_f32 v[60:61], v[94:95], v[14:15], v[60:61] neg_lo:[0,0,1] neg_hi:[0,0,1]
	v_pk_mul_f32 v[14:15], v[16:17], v[14:15]
	v_pk_mul_f32 v[16:17], v[80:81], v[70:71] op_sel_hi:[1,0]
	v_pk_fma_f32 v[62:63], v[94:95], v[62:63], v[14:15]
	v_pk_mul_f32 v[14:15], v[72:73], v[70:71] op_sel_hi:[1,0]
	v_pk_mul_f32 v[16:17], v[16:17], v[56:57]
	v_pk_mul_f32 v[14:15], v[14:15], v[58:59]
	v_pk_mul_f32 v[56:57], v[96:97], v[16:17]
	v_cvt_pk_bf16_f32 v94, v64, v65
	v_pk_fma_f32 v[56:57], v[88:89], v[14:15], v[56:57] neg_lo:[0,0,1] neg_hi:[0,0,1]
	v_pk_mul_f32 v[14:15], v[96:97], v[14:15]
	v_cvt_pk_bf16_f32 v95, v60, v61
	v_pk_fma_f32 v[58:59], v[88:89], v[16:17], v[14:15]
	v_pk_mul_f32 v[16:17], v[82:83], v[70:71] op_sel_hi:[1,0]
	v_pk_mul_f32 v[14:15], v[74:75], v[70:71] op_sel_hi:[1,0]
	v_pk_mul_f32 v[16:17], v[16:17], v[24:25]
	v_pk_mul_f32 v[14:15], v[14:15], v[54:55]
	v_pk_mul_f32 v[24:25], v[98:99], v[16:17]
	v_cvt_pk_bf16_f32 v92, v58, v59
	v_pk_fma_f32 v[54:55], v[90:91], v[14:15], v[24:25] neg_lo:[0,0,1] neg_hi:[0,0,1]
	v_pk_mul_f32 v[14:15], v[98:99], v[14:15]
	v_cvt_pk_bf16_f32 v96, v56, v57
	v_pk_fma_f32 v[68:69], v[90:91], v[16:17], v[14:15]
	global_load_dwordx4 v[14:17], v[22:23], off offset:80
	global_load_dwordx4 v[72:75], v[22:23], off offset:64
	s_nop 0
	global_load_dwordx4 v[22:25], v[42:43], off offset:16
	global_load_dwordx4 v[76:79], v[42:43], off
	v_pk_mul_f32 v[42:43], v[26:27], v[52:53]
	v_pk_mul_f32 v[26:27], v[30:31], v[70:71] op_sel_hi:[1,0]
	s_nop 0
	v_pk_mul_f32 v[30:31], v[26:27], v[50:51]
	s_barrier
	ds_write_b128 v45, v[2:5]
	ds_write2_b64 v71, v[6:7], v[8:9] offset1:1
	v_mov_b32_e32 v45, v1
	v_lshl_add_u64 v[2:3], s[20:21], 0, v[44:45]
	s_add_u32 s20, s45, s22
	v_lshl_add_u64 v[2:3], v[2:3], 0, v[134:135]
	s_addc_u32 s21, 0, 0
	v_lshl_add_u64 v[114:115], s[4:5], 0, v[2:3]
	v_lshl_add_u64 v[2:3], s[20:21], 0, v[134:135]
	v_readlane_b32 s4, v249, 1
	v_lshl_add_u64 v[2:3], v[2:3], 0, v[0:1]
	v_readlane_b32 s5, v249, 2
	s_waitcnt lgkmcnt(0)
	s_barrier
; template <bool TRACK> ...
;     ...
;     f32x16 o0, o1;
; #pragma unroll
;     for (int r = 0; r < 16; ++r) { o0[r] = 0.f; o1[r] = 0.f; }
;     float m = m_init, lsum = hi == 0 ? l_init : 0.f;
;     f32x16 negm, lacc;
; #pragma unroll
;     for (int r = 0; r < 16; ++r) { negm[r] = TRACK ? -m_init : 0.f; lacc[r] = TRACK ? 0.f : l_init * __builtin_amdgcn_exp2f(m_init); }
;     const bf16x8 ones = __builtin_bit_cast(bf16x8, ((u32x4){0x3f803f80u, 0x3f803f80u, 0x3f803f80u, 0x3f803f80u}));
;     for (int j = 0; j < nt; ++j) {
;         const int cur = j & 1; const int tl = j < n0 ? j : t1lo + (j - n0);
;         if (j + 1 < nt) { const int tn = (j + 1) < n0 ? (j + 1) : t1lo + (j + 1 - n0);
;             kreg = *(const u32x4*)(Kb + (size_t)(tn * 64 + srow) * 64 + sc * 8); vreg = *(const u32x4*)(Vtb + (size_t)srow * KEYS + tn * 64 + sc * 8); }
;         bool active = true; bool mt = masked && j >= n0; const int kpos0 = (tl - 4) * 64;
;         if (mt) { const int qs = qstart + wave * 32; active = !(kpos0 > qs + 31 + 128 || kpos0 + 63 < qs - 128);
;             if (kpos0 >= qs + 31 - 128 && kpos0 + 63 <= qs + 128) mt = false; }
;         if (active) {
;             const LAS unsigned char* Kbuf = lds + cur * 18432; const LAS unsigned char* Vbuf = Kbuf + 9216;
;             f32x16 s0 = negm, s1 = negm;
;             u32x2 vq[8];
;             if constexpr (!TRACK) {
;             bf16x8 kf[8];
; #pragma unroll
;             for (int d = 0; d < 4; ++d) { kf[2 * d] = *(const LAS bf16x8*)(Kbuf + (r32 * 72 + d * 16 + hi * 8) * 2); kf[2 * d + 1] = *(const LAS bf16x8*)(Kbuf + ((32 + r32) * 72 + d * 16 + hi * 8) * 2); }
;             __builtin_amdgcn_sched_barrier(0);
; #pragma unroll
;             for (int d = 0; d < 4; ++d) {
;                 s0 = __builtin_amdgcn_mfma_f32_32x32x16_bf16(kf[2 * d], qf[d], s0, 0, 0, 0);
;                 s1 = __builtin_amdgcn_mfma_f32_32x32x16_bf16(kf[2 * d + 1], qf[d], s1, 0, 0, 0);
;             }
; #pragma unroll
;             for (int kc = 0; kc < 2; ++kc) {
;                 const LAS unsigned char* vp0 = Vbuf + (r32 * 68 + kc * 16 + 4 * hi) * 2; const LAS unsigned char* vp1 = vp0 + 32 * 68 * 2;
;                 vq[4 * kc] = *(const LAS u32x2*)vp0; vq[4 * kc + 1] = *(const LAS u32x2*)(vp0 + 16); vq[4 * kc + 2] = *(const LAS u32x2*)vp1; vq[4 * kc + 3] = *(const LAS u32x2*)(vp1 + 16); }
;             __builtin_amdgcn_sched_barrier(0);
	v_lshl_add_u64 v[116:117], s[4:5], 0, v[2:3]
	global_load_dwordx4 v[230:233], v[114:115], off
	v_mov_b32_e32 v2, 0
	v_cvt_pk_bf16_f32 v90, v66, v67
	v_cvt_pk_bf16_f32 v91, v62, v63
	v_cvt_pk_bf16_f32 v93, v68, v69
	v_cvt_pk_bf16_f32 v97, v54, v55
	s_mov_b32 s20, 0
	v_mov_b32_e32 v3, v2
	v_mov_b32_e32 v4, v2
	v_mov_b32_e32 v5, v2
	v_mov_b32_e32 v6, v2
	v_mov_b32_e32 v7, v2
	v_mov_b32_e32 v8, v2
	v_mov_b32_e32 v9, v2
	v_mov_b32_e32 v36, v2
	v_mov_b32_e32 v37, v2
	v_mov_b32_e32 v38, v2
	v_mov_b32_e32 v39, v2
	v_mov_b32_e32 v44, v2
	v_mov_b32_e32 v45, v2
	s_mov_b64 s[4:5], 0x2000
	s_waitcnt vmcnt(2)
	v_pk_mul_f32 v[10:11], v[40:41], v[22:23]
	s_waitcnt vmcnt(1)
	v_pk_mul_f32 v[26:27], v[42:43], v[76:77]
	v_pk_fma_f32 v[10:11], v[18:19], v[14:15], v[10:11] neg_lo:[0,0,1] neg_hi:[0,0,1]
	v_pk_fma_f32 v[26:27], v[30:31], v[72:73], v[26:27] neg_lo:[0,0,1] neg_hi:[0,0,1]
	v_pk_mul_f32 v[30:31], v[30:31], v[76:77]
	v_pk_mul_f32 v[18:19], v[18:19], v[22:23]
	v_pk_fma_f32 v[30:31], v[42:43], v[72:73], v[30:31]
	v_pk_mul_f32 v[42:43], v[28:29], v[48:49]
	v_pk_mul_f32 v[28:29], v[32:33], v[70:71] op_sel_hi:[1,0]
	v_pk_fma_f32 v[14:15], v[40:41], v[14:15], v[18:19]
	v_pk_mul_f32 v[18:19], v[20:21], v[70:71] op_sel_hi:[1,0]
	v_pk_mul_f32 v[32:33], v[28:29], v[46:47]
	v_pk_mul_f32 v[28:29], v[42:43], v[78:79]
	v_pk_mul_f32 v[18:19], v[18:19], v[34:35]
	v_pk_mul_f32 v[20:21], v[12:13], v[24:25]
	v_pk_fma_f32 v[28:29], v[32:33], v[74:75], v[28:29] neg_lo:[0,0,1] neg_hi:[0,0,1]
	v_pk_mul_f32 v[32:33], v[32:33], v[78:79]
	v_pk_fma_f32 v[20:21], v[18:19], v[16:17], v[20:21] neg_lo:[0,0,1] neg_hi:[0,0,1]
	v_pk_mul_f32 v[18:19], v[18:19], v[24:25]
	v_pk_fma_f32 v[32:33], v[42:43], v[74:75], v[32:33]
	v_pk_fma_f32 v[12:13], v[12:13], v[16:17], v[18:19]
	v_cvt_pk_bf16_f32 v82, v30, v31
	v_cvt_pk_bf16_f32 v83, v32, v33
	v_cvt_pk_bf16_f32 v84, v14, v15
	v_cvt_pk_bf16_f32 v85, v12, v13
	v_cvt_pk_bf16_f32 v86, v26, v27
	v_cvt_pk_bf16_f32 v87, v28, v29
	v_cvt_pk_bf16_f32 v88, v10, v11
	v_cvt_pk_bf16_f32 v89, v20, v21
	v_mov_b32_e32 v10, v2
	v_mov_b32_e32 v11, v2
	v_mov_b32_e32 v12, v2
	v_mov_b32_e32 v13, v2
	v_mov_b32_e32 v14, v2
	v_mov_b32_e32 v15, v2
	v_mov_b32_e32 v16, v2
	v_mov_b32_e32 v17, v2
	v_mov_b32_e32 v18, v2
	v_mov_b32_e32 v19, v2
	v_mov_b32_e32 v20, v2
	v_mov_b32_e32 v21, v2
	v_mov_b32_e32 v22, v2
	v_mov_b32_e32 v23, v2
	v_mov_b32_e32 v24, v2
	v_mov_b32_e32 v25, v2
	v_mov_b32_e32 v26, v2
	v_mov_b32_e32 v27, v2
	v_mov_b32_e32 v28, v2
	v_mov_b32_e32 v29, v2
	v_mov_b32_e32 v30, v2
	v_mov_b32_e32 v31, v2
	v_mov_b32_e32 v32, v2
	v_mov_b32_e32 v33, v2
	v_mov_b32_e32 v34, v2
	v_mov_b32_e32 v35, v2
	v_mov_b32_e32 v40, v2
	v_mov_b32_e32 v41, v2
	v_mov_b32_e32 v42, v2
	v_mov_b32_e32 v43, v2
	v_mov_b32_e32 v46, v2
	v_mov_b32_e32 v47, v2
	v_mov_b32_e32 v48, v2
	v_mov_b32_e32 v49, v2
	s_waitcnt vmcnt(0)
	ds_write_b128 v201, v[230:233] offset:18432
	v_lshl_add_u64 v[114:115], v[114:115], 0, s[4:5]
	v_add_u32_e32 v246, v199, v200
	v_add_u32_e32 v127, 0x6c00, v203
	v_add_u32_e32 v129, 0x2400, v203
	v_mov_b32_e32 v118, s88
	v_mov_b32_e32 v119, s88
	v_mov_b32_e32 v120, s88
	v_mov_b32_e32 v121, s88
	v_add_u32_e32 v247, 0x2000, v246
	v_add_u32_e32 v0, 0x3000, v246
	v_add_u32_e32 v123, 0x6800, v246
	v_add_u32_e32 v125, 0x7800, v246
	s_waitcnt lgkmcnt(0)
	ds_read_b128 v[214:217], v204 offset:0
	ds_read_b128 v[218:221], v202 offset:0
	ds_read_b128 v[222:225], v204 offset:32
	ds_read_b128 v[226:229], v202 offset:32
	ds_read_b128 v[230:233], v204 offset:64
	ds_read_b128 v[234:237], v202 offset:64
	ds_read_b128 v[238:241], v204 offset:96
	ds_read_b128 v[242:245], v202 offset:96
	s_waitcnt lgkmcnt(7)
	v_mfma_f32_32x32x16_bf16 v[50:65], v[214:217], v[94:97], 0
	s_waitcnt lgkmcnt(6)
	v_mfma_f32_32x32x16_bf16 v[66:81], v[218:221], v[94:97], 0
	s_waitcnt lgkmcnt(5)
	v_mfma_f32_32x32x16_bf16 v[50:65], v[222:225], v[90:93], v[50:65]
	s_waitcnt lgkmcnt(4)
	v_mfma_f32_32x32x16_bf16 v[66:81], v[226:229], v[90:93], v[66:81]
	s_waitcnt lgkmcnt(3)
	v_mfma_f32_32x32x16_bf16 v[50:65], v[230:233], v[86:89], v[50:65]
	s_waitcnt lgkmcnt(2)
	v_mfma_f32_32x32x16_bf16 v[66:81], v[234:237], v[86:89], v[66:81]
	s_waitcnt lgkmcnt(1)
	v_mfma_f32_32x32x16_bf16 v[50:65], v[238:241], v[82:85], v[50:65]
	s_waitcnt lgkmcnt(0)
	v_mfma_f32_32x32x16_bf16 v[66:81], v[242:245], v[82:85], v[66:81]
	s_barrier
	s_nop 15
	v_exp_f32_e32 v50, v50
	v_exp_f32_e32 v51, v51
	v_exp_f32_e32 v52, v52
	v_exp_f32_e32 v53, v53
	v_exp_f32_e32 v54, v54
	v_exp_f32_e32 v55, v55
	v_exp_f32_e32 v56, v56
	v_exp_f32_e32 v57, v57
	v_cvt_pk_bf16_f32 v50, v50, v51
	v_cvt_pk_bf16_f32 v51, v52, v53
	v_cvt_pk_bf16_f32 v52, v54, v55
	v_cvt_pk_bf16_f32 v53, v56, v57
	v_readfirstlane_b32 s4, v114
	v_readfirstlane_b32 s5, v115
	v_readfirstlane_b32 s38, v116
	v_readfirstlane_b32 s39, v117
	s_nop 4
	v_subrev_u32_e32 v114, s4, v114
	v_subrev_u32_e32 v116, s38, v116
	s_nop 1
; template <bool TRACK> ...
;     ...
;         const int cur = j & 1; const int tl = j < n0 ? j : t1lo + (j - n0);
;         if (j + 1 < nt) { const int tn = (j + 1) < n0 ? (j + 1) : t1lo + (j + 1 - n0);
;             kreg = *(const u32x4*)(Kb + (size_t)(tn * 64 + srow) * 64 + sc * 8); vreg = *(const u32x4*)(Vtb + (size_t)srow * KEYS + tn * 64 + sc * 8); }
;         bool active = true; bool mt = masked && j >= n0; const int kpos0 = (tl - 4) * 64;
;         if (mt) { const int qs = qstart + wave * 32; active = !(kpos0 > qs + 31 + 128 || kpos0 + 63 < qs - 128);
;             if (kpos0 >= qs + 31 - 128 && kpos0 + 63 <= qs + 128) mt = false; }
;         if (active) {
;             const LAS unsigned char* Kbuf = lds + cur * 18432; const LAS unsigned char* Vbuf = Kbuf + 9216;
;             f32x16 s0 = negm, s1 = negm;
;             u32x2 vq[8];
;             if constexpr (!TRACK) {
;             bf16x8 kf[8];
; #pragma unroll
;             for (int d = 0; d < 4; ++d) { kf[2 * d] = *(const LAS bf16x8*)(Kbuf + (r32 * 72 + d * 16 + hi * 8) * 2); kf[2 * d + 1] = *(const LAS bf16x8*)(Kbuf + ((32 + r32) * 72 + d * 16 + hi * 8) * 2); }
;             __builtin_amdgcn_sched_barrier(0);
; #pragma unroll
;             for (int d = 0; d < 4; ++d) {
;                 s0 = __builtin_amdgcn_mfma_f32_32x32x16_bf16(kf[2 * d], qf[d], s0, 0, 0, 0);
;                 s1 = __builtin_amdgcn_mfma_f32_32x32x16_bf16(kf[2 * d + 1], qf[d], s1, 0, 0, 0);
;             }
; #pragma unroll
;             for (int kc = 0; kc < 2; ++kc) {
;                 const LAS unsigned char* vp0 = Vbuf + (r32 * 68 + kc * 16 + 4 * hi) * 2; const LAS unsigned char* vp1 = vp0 + 32 * 68 * 2;
;                 vq[4 * kc] = *(const LAS u32x2*)vp0; vq[4 * kc + 1] = *(const LAS u32x2*)(vp0 + 16); vq[4 * kc + 2] = *(const LAS u32x2*)vp1; vq[4 * kc + 3] = *(const LAS u32x2*)(vp1 + 16); }
;             __builtin_amdgcn_sched_barrier(0);
;             } else {
; #pragma unroll
;             for (int d = 0; d < 4; ++d) {
;                 const bf16x8 a0 = *(const LAS bf16x8*)(Kbuf + (r32 * 72 + d * 16 + hi * 8) * 2);
;                 const bf16x8 a1 = *(const LAS bf16x8*)(Kbuf + ((32 + r32) * 72 + d * 16 + hi * 8) * 2);
;                 s0 = __builtin_amdgcn_mfma_f32_32x32x16_bf16(a0, qf[d], s0, 0, 0, 0);
;                 s1 = __builtin_amdgcn_mfma_f32_32x32x16_bf16(a1, qf[d], s1, 0, 0, 0);
;             }
;     ...
; #pragma unroll
.LBB0_167:
	global_load_dwordx4 v[98:101], v114, s[4:5]
	global_load_dwordx4 v[102:105], v116, s[38:39]
	ds_read_b128 v[106:109], v204 offset:18432
	ds_read_b128 v[110:113], v202 offset:18432
	ds_read_b128 v[158:161], v204 offset:18464
	ds_read2_b64 v[206:209], v247 offset0:128 offset1:130
	ds_read2_b64 v[210:213], v0 offset0:160 offset1:162
	s_add_u32 s4, s4, 0x2000
	s_addc_u32 s5, s5, 0
	s_add_u32 s38, s38, 0x80
	s_addc_u32 s39, s39, 0
	s_waitcnt lgkmcnt(4)
	v_mfma_f32_32x32x16_bf16 v[214:229], v[106:109], v[94:97], 0
	ds_read_b128 v[106:109], v202 offset:18464
	v_exp_f32_e32 v58, v58
	v_exp_f32_e32 v59, v59
	v_exp_f32_e32 v60, v60
	s_waitcnt lgkmcnt(4)
	v_mfma_f32_32x32x16_bf16 v[230:245], v[110:113], v[94:97], 0
	ds_read_b128 v[110:113], v204 offset:18496
	v_exp_f32_e32 v61, v61
	v_exp_f32_e32 v62, v62
	v_exp_f32_e32 v63, v63
	s_waitcnt lgkmcnt(4)
	v_mfma_f32_32x32x16_bf16 v[214:229], v[158:161], v[90:93], v[214:229]
	ds_read_b128 v[158:161], v202 offset:18496
	v_exp_f32_e32 v64, v64
	v_exp_f32_e32 v65, v65
	v_cvt_pk_bf16_f32 v54, v58, v59
	s_waitcnt lgkmcnt(2)
	v_mfma_f32_32x32x16_bf16 v[230:245], v[106:109], v[90:93], v[230:245]
	ds_read_b128 v[106:109], v204 offset:18528
	v_cvt_pk_bf16_f32 v55, v60, v61
	v_cvt_pk_bf16_f32 v56, v62, v63
	v_cvt_pk_bf16_f32 v57, v64, v65
	s_waitcnt lgkmcnt(2)
	v_mfma_f32_32x32x16_bf16 v[214:229], v[110:113], v[86:89], v[214:229]
	ds_read_b128 v[110:113], v202 offset:18528
	v_exp_f32_e32 v66, v66
	v_exp_f32_e32 v67, v67
	v_exp_f32_e32 v68, v68
	s_waitcnt lgkmcnt(2)
	v_mfma_f32_32x32x16_bf16 v[230:245], v[158:161], v[86:89], v[230:245]
	v_exp_f32_e32 v69, v69
	v_exp_f32_e32 v70, v70
	v_exp_f32_e32 v71, v71
	s_waitcnt lgkmcnt(1)
	v_mfma_f32_32x32x16_bf16 v[214:229], v[106:109], v[82:85], v[214:229]
	v_exp_f32_e32 v72, v72
	v_exp_f32_e32 v73, v73
	v_cvt_pk_bf16_f32 v66, v66, v67
	s_waitcnt lgkmcnt(0)
	v_mfma_f32_32x32x16_bf16 v[230:245], v[110:113], v[82:85], v[230:245]
	v_cvt_pk_bf16_f32 v67, v68, v69
	v_cvt_pk_bf16_f32 v68, v70, v71
	v_cvt_pk_bf16_f32 v69, v72, v73
	v_mfma_f32_32x32x16_bf16 v[2:17], v[206:209], v[50:53], v[2:17]
	ds_read2_b64 v[206:209], v247 offset0:132 offset1:134
	v_exp_f32_e32 v74, v74
	v_exp_f32_e32 v75, v75
	v_exp_f32_e32 v76, v76
	v_mfma_f32_32x32x16_bf16 v[18:33], v[210:213], v[50:53], v[18:33]
	ds_read2_b64 v[210:213], v0 offset0:164 offset1:166
	v_exp_f32_e32 v77, v77
	v_exp_f32_e32 v78, v78
	v_exp_f32_e32 v79, v79
	v_mfma_f32_4x4x4_16b_bf16 v[34:37], v[118:119], v[50:51], v[34:37]
	v_mfma_f32_4x4x4_16b_bf16 v[38:41], v[118:119], v[52:53], v[38:41]
	v_exp_f32_e32 v80, v80
	v_exp_f32_e32 v81, v81
	s_waitcnt lgkmcnt(1)
	v_mfma_f32_32x32x16_bf16 v[2:17], v[206:209], v[54:57], v[2:17]
	ds_read2_b64 v[206:209], v247 offset0:136 offset1:138
	v_cvt_pk_bf16_f32 v70, v74, v75
	v_cvt_pk_bf16_f32 v71, v76, v77
	v_cvt_pk_bf16_f32 v72, v78, v79
	s_waitcnt lgkmcnt(1)
	v_mfma_f32_32x32x16_bf16 v[18:33], v[210:213], v[54:57], v[18:33]
	ds_read2_b64 v[210:213], v0 offset0:168 offset1:170
	v_cvt_pk_bf16_f32 v73, v80, v81
	v_mfma_f32_4x4x4_16b_bf16 v[34:37], v[118:119], v[54:55], v[34:37]
	v_mfma_f32_4x4x4_16b_bf16 v[38:41], v[118:119], v[56:57], v[38:41]
	s_waitcnt vmcnt(1)
	ds_write_b128 v201, v[98:101] offset:0
	s_waitcnt vmcnt(0)
	ds_write2_b64 v127, v[102:103], v[104:105] offset1:1
	s_waitcnt lgkmcnt(3)
	v_mfma_f32_32x32x16_bf16 v[2:17], v[206:209], v[66:69], v[2:17]
	ds_read2_b64 v[206:209], v247 offset0:140 offset1:142
	v_exp_f32_e32 v214, v214
	v_exp_f32_e32 v215, v215
	v_exp_f32_e32 v216, v216
	s_waitcnt lgkmcnt(3)
	v_mfma_f32_32x32x16_bf16 v[18:33], v[210:213], v[66:69], v[18:33]
	ds_read2_b64 v[210:213], v0 offset0:172 offset1:174
	v_exp_f32_e32 v217, v217
	v_exp_f32_e32 v218, v218
	v_mfma_f32_4x4x4_16b_bf16 v[34:37], v[118:119], v[66:67], v[34:37]
	v_mfma_f32_4x4x4_16b_bf16 v[38:41], v[118:119], v[68:69], v[38:41]
	s_waitcnt lgkmcnt(1)
	v_mfma_f32_32x32x16_bf16 v[2:17], v[206:209], v[70:73], v[2:17]
	v_exp_f32_e32 v219, v219
	v_exp_f32_e32 v220, v220
	v_exp_f32_e32 v221, v221
	s_waitcnt lgkmcnt(0)
	v_mfma_f32_32x32x16_bf16 v[18:33], v[210:213], v[70:73], v[18:33]
	v_cvt_pk_bf16_f32 v214, v214, v215
	v_cvt_pk_bf16_f32 v215, v216, v217
	v_cvt_pk_bf16_f32 v216, v218, v219
	v_mfma_f32_4x4x4_16b_bf16 v[34:37], v[118:119], v[70:71], v[34:37]
	v_mfma_f32_4x4x4_16b_bf16 v[38:41], v[118:119], v[72:73], v[38:41]
	v_cvt_pk_bf16_f32 v217, v220, v221
	s_waitcnt lgkmcnt(0)
	s_barrier
; template <bool TRACK> ...
;     ...
;         const int cur = j & 1; const int tl = j < n0 ? j : t1lo + (j - n0);
;         if (j + 1 < nt) { const int tn = (j + 1) < n0 ? (j + 1) : t1lo + (j + 1 - n0);
;             kreg = *(const u32x4*)(Kb + (size_t)(tn * 64 + srow) * 64 + sc * 8); vreg = *(const u32x4*)(Vtb + (size_t)srow * KEYS + tn * 64 + sc * 8); }
;         bool active = true; bool mt = masked && j >= n0; const int kpos0 = (tl - 4) * 64;
;         if (mt) { const int qs = qstart + wave * 32; active = !(kpos0 > qs + 31 + 128 || kpos0 + 63 < qs - 128);
;             if (kpos0 >= qs + 31 - 128 && kpos0 + 63 <= qs + 128) mt = false; }
;         if (active) {
;             const LAS unsigned char* Kbuf = lds + cur * 18432; const LAS unsigned char* Vbuf = Kbuf + 9216;
;             f32x16 s0 = negm, s1 = negm;
;             u32x2 vq[8];
;             if constexpr (!TRACK) {
;             bf16x8 kf[8];
; #pragma unroll
;             for (int d = 0; d < 4; ++d) { kf[2 * d] = *(const LAS bf16x8*)(Kbuf + (r32 * 72 + d * 16 + hi * 8) * 2); kf[2 * d + 1] = *(const LAS bf16x8*)(Kbuf + ((32 + r32) * 72 + d * 16 + hi * 8) * 2); }
;             __builtin_amdgcn_sched_barrier(0);
; #pragma unroll
;             for (int d = 0; d < 4; ++d) {
;                 s0 = __builtin_amdgcn_mfma_f32_32x32x16_bf16(kf[2 * d], qf[d], s0, 0, 0, 0);
;                 s1 = __builtin_amdgcn_mfma_f32_32x32x16_bf16(kf[2 * d + 1], qf[d], s1, 0, 0, 0);
;             }
; #pragma unroll
;             for (int kc = 0; kc < 2; ++kc) {
;                 const LAS unsigned char* vp0 = Vbuf + (r32 * 68 + kc * 16 + 4 * hi) * 2; const LAS unsigned char* vp1 = vp0 + 32 * 68 * 2;
;                 vq[4 * kc] = *(const LAS u32x2*)vp0; vq[4 * kc + 1] = *(const LAS u32x2*)(vp0 + 16); vq[4 * kc + 2] = *(const LAS u32x2*)vp1; vq[4 * kc + 3] = *(const LAS u32x2*)(vp1 + 16); }
;             __builtin_amdgcn_sched_barrier(0);
;             } else {
; #pragma unroll
;             for (int d = 0; d < 4; ++d) {
;                 const bf16x8 a0 = *(const LAS bf16x8*)(Kbuf + (r32 * 72 + d * 16 + hi * 8) * 2);
;                 const bf16x8 a1 = *(const LAS bf16x8*)(Kbuf + ((32 + r32) * 72 + d * 16 + hi * 8) * 2);
;                 s0 = __builtin_amdgcn_mfma_f32_32x32x16_bf16(a0, qf[d], s0, 0, 0, 0);
;                 s1 = __builtin_amdgcn_mfma_f32_32x32x16_bf16(a1, qf[d], s1, 0, 0, 0);
;             }
;     ...
; #pragma unroll
	global_load_dwordx4 v[98:101], v114, s[4:5]
	global_load_dwordx4 v[102:105], v116, s[38:39]
	ds_read_b128 v[106:109], v204 offset:0
	ds_read_b128 v[110:113], v202 offset:0
	ds_read_b128 v[158:161], v204 offset:32
	ds_read2_b64 v[206:209], v123 offset0:128 offset1:130
	ds_read2_b64 v[210:213], v125 offset0:160 offset1:162
	s_add_u32 s4, s4, 0x2000
	s_addc_u32 s5, s5, 0
	s_add_u32 s38, s38, 0x80
	s_addc_u32 s39, s39, 0
	s_waitcnt lgkmcnt(4)
	v_mfma_f32_32x32x16_bf16 v[50:65], v[106:109], v[94:97], 0
	ds_read_b128 v[106:109], v202 offset:32
	v_exp_f32_e32 v222, v222
	v_exp_f32_e32 v223, v223
	v_exp_f32_e32 v224, v224
	s_waitcnt lgkmcnt(4)
	v_mfma_f32_32x32x16_bf16 v[66:81], v[110:113], v[94:97], 0
	ds_read_b128 v[110:113], v204 offset:64
	v_exp_f32_e32 v225, v225
	v_exp_f32_e32 v226, v226
	v_exp_f32_e32 v227, v227
	s_waitcnt lgkmcnt(4)
	v_mfma_f32_32x32x16_bf16 v[50:65], v[158:161], v[90:93], v[50:65]
	ds_read_b128 v[158:161], v202 offset:64
	v_exp_f32_e32 v228, v228
	v_exp_f32_e32 v229, v229
	v_cvt_pk_bf16_f32 v218, v222, v223
	s_waitcnt lgkmcnt(2)
	v_mfma_f32_32x32x16_bf16 v[66:81], v[106:109], v[90:93], v[66:81]
	ds_read_b128 v[106:109], v204 offset:96
	v_cvt_pk_bf16_f32 v219, v224, v225
	v_cvt_pk_bf16_f32 v220, v226, v227
	v_cvt_pk_bf16_f32 v221, v228, v229
	s_waitcnt lgkmcnt(2)
	v_mfma_f32_32x32x16_bf16 v[50:65], v[110:113], v[86:89], v[50:65]
	ds_read_b128 v[110:113], v202 offset:96
	v_exp_f32_e32 v230, v230
	v_exp_f32_e32 v231, v231
	v_exp_f32_e32 v232, v232
	s_waitcnt lgkmcnt(2)
	v_mfma_f32_32x32x16_bf16 v[66:81], v[158:161], v[86:89], v[66:81]
	v_exp_f32_e32 v233, v233
	v_exp_f32_e32 v234, v234
	v_exp_f32_e32 v235, v235
	s_waitcnt lgkmcnt(1)
	v_mfma_f32_32x32x16_bf16 v[50:65], v[106:109], v[82:85], v[50:65]
	v_exp_f32_e32 v236, v236
	v_exp_f32_e32 v237, v237
	v_cvt_pk_bf16_f32 v230, v230, v231
	s_waitcnt lgkmcnt(0)
	v_mfma_f32_32x32x16_bf16 v[66:81], v[110:113], v[82:85], v[66:81]
	v_cvt_pk_bf16_f32 v231, v232, v233
	v_cvt_pk_bf16_f32 v232, v234, v235
	v_cvt_pk_bf16_f32 v233, v236, v237
	v_mfma_f32_32x32x16_bf16 v[2:17], v[206:209], v[214:217], v[2:17]
	ds_read2_b64 v[206:209], v123 offset0:132 offset1:134
	v_exp_f32_e32 v238, v238
	v_exp_f32_e32 v239, v239
	v_exp_f32_e32 v240, v240
	v_mfma_f32_32x32x16_bf16 v[18:33], v[210:213], v[214:217], v[18:33]
	ds_read2_b64 v[210:213], v125 offset0:164 offset1:166
	v_exp_f32_e32 v241, v241
	v_exp_f32_e32 v242, v242
	v_exp_f32_e32 v243, v243
	v_mfma_f32_4x4x4_16b_bf16 v[34:37], v[118:119], v[214:215], v[34:37]
	v_mfma_f32_4x4x4_16b_bf16 v[38:41], v[118:119], v[216:217], v[38:41]
	v_exp_f32_e32 v244, v244
	v_exp_f32_e32 v245, v245
	s_waitcnt lgkmcnt(1)
	v_mfma_f32_32x32x16_bf16 v[2:17], v[206:209], v[218:221], v[2:17]
	ds_read2_b64 v[206:209], v123 offset0:136 offset1:138
	v_cvt_pk_bf16_f32 v234, v238, v239
	v_cvt_pk_bf16_f32 v235, v240, v241
	v_cvt_pk_bf16_f32 v236, v242, v243
	s_waitcnt lgkmcnt(1)
	v_mfma_f32_32x32x16_bf16 v[18:33], v[210:213], v[218:221], v[18:33]
	ds_read2_b64 v[210:213], v125 offset0:168 offset1:170
	v_cvt_pk_bf16_f32 v237, v244, v245
	v_mfma_f32_4x4x4_16b_bf16 v[34:37], v[118:119], v[218:219], v[34:37]
	v_mfma_f32_4x4x4_16b_bf16 v[38:41], v[118:119], v[220:221], v[38:41]
	s_waitcnt vmcnt(1)
	ds_write_b128 v201, v[98:101] offset:18432
	s_waitcnt vmcnt(0)
	ds_write2_b64 v129, v[102:103], v[104:105] offset1:1
	s_waitcnt lgkmcnt(3)
	v_mfma_f32_32x32x16_bf16 v[2:17], v[206:209], v[230:233], v[2:17]
	ds_read2_b64 v[206:209], v123 offset0:140 offset1:142
	v_exp_f32_e32 v50, v50
	v_exp_f32_e32 v51, v51
	v_exp_f32_e32 v52, v52
	s_waitcnt lgkmcnt(3)
	v_mfma_f32_32x32x16_bf16 v[18:33], v[210:213], v[230:233], v[18:33]
	ds_read2_b64 v[210:213], v125 offset0:172 offset1:174
	v_exp_f32_e32 v53, v53
	v_exp_f32_e32 v54, v54
	v_mfma_f32_4x4x4_16b_bf16 v[34:37], v[118:119], v[230:231], v[34:37]
	v_mfma_f32_4x4x4_16b_bf16 v[38:41], v[118:119], v[232:233], v[38:41]
	s_waitcnt lgkmcnt(1)
	v_mfma_f32_32x32x16_bf16 v[2:17], v[206:209], v[234:237], v[2:17]
	v_exp_f32_e32 v55, v55
	v_exp_f32_e32 v56, v56
	v_exp_f32_e32 v57, v57
	s_waitcnt lgkmcnt(0)
	v_mfma_f32_32x32x16_bf16 v[18:33], v[210:213], v[234:237], v[18:33]
	v_cvt_pk_bf16_f32 v50, v50, v51
	v_cvt_pk_bf16_f32 v51, v52, v53
	v_cvt_pk_bf16_f32 v52, v54, v55
	v_mfma_f32_4x4x4_16b_bf16 v[34:37], v[118:119], v[234:235], v[34:37]
	v_mfma_f32_4x4x4_16b_bf16 v[38:41], v[118:119], v[236:237], v[38:41]
	v_cvt_pk_bf16_f32 v53, v56, v57
	s_add_i32 s20, s20, 2
	s_cmp_lg_u32 s20, 36
	s_waitcnt lgkmcnt(0)
	s_barrier
	s_cbranch_scc1 .LBB0_167
	global_load_dwordx4 v[214:217], v[154:155], off offset:1280
	global_load_dwordx4 v[218:221], v[150:151], off offset:1280
	global_load_dwordx4 v[222:225], v[142:143], off offset:1280
	global_load_dwordx4 v[226:229], v[138:139], off offset:1280
	s_mov_b64 s[4:5], 0x2000
	s_mov_b64 s[38:39], 0x80
	s_nop 15
	v_readlane_b32 s89, v248, 3
	v_add_f32_e32 v34, v34, v38
	s_nop 0
	ds_bpermute_b32 v35, v188, v34
	s_waitcnt lgkmcnt(0)
	v_add_f32_e32 v34, v34, v35
	s_nop 0
	v_div_scale_f32 v0, s[20:21], v34, v34, 1.0
	v_rcp_f32_e32 v35, v0
	s_waitcnt lgkmcnt(0)
	s_barrier
; #define LAS __attribute__((address_space(3)))
; __device__ __forceinline__ unsigned pk2(float lo, float hi) { f32x2_t v = {lo, hi}; bf16x2_t b = __builtin_convertvector(v, bf16x2_t); return __builtin_bit_cast(unsigned, b); }
; __device__ __forceinline__ float silu_f(float v) { return v * __builtin_amdgcn_rcpf(1.0f + __expf(-v)); }
; template <bool TRACK> ...
;     ...
;     const float ltot = TRACK ? lsum + __shfl_xor(lsum, 32) : lacc[0]; const float inv = 1.0f / ltot;
;     {
;         LAS unsigned char* scr = lds + 40960 + wave * 8704;
; #pragma unroll
;         for (int dh = 0; dh < 2; ++dh)
; #pragma unroll
;             for (int rg = 0; rg < 4; ++rg) { const int d = dh * 32 + 8 * rg + 4 * hi;
;                 f32x4 ov; ov.x = (dh == 0 ? o0[4 * rg] : o1[4 * rg]) * inv; ov.y = (dh == 0 ? o0[4 * rg + 1] : o1[4 * rg + 1]) * inv; ov.z = (dh == 0 ? o0[4 * rg + 2] : o1[4 * rg + 2]) * inv; ov.w = (dh == 0 ? o0[4 * rg + 3] : o1[4 * rg + 3]) * inv;
;                 *(LAS f32x4*)(scr + r32 * 272 + d * 4) = ov; }
;         const int pc = lane & 7;
; #pragma unroll
;         for (int i = 0; i < 4; ++i) { const int rw = i * 8 + (lane >> 3), row = wave * 32 + rw;
;             const f32x4 oa = *(const LAS f32x4*)(scr + rw * 272 + pc * 32), ob = *(const LAS f32x4*)(scr + rw * 272 + pc * 32 + 16);
;             float gv[8]; unpack8(*(const u32x4*)(gate + (size_t)row * INW + 8 * pc), gv);
;             u32x4 w; w.x = pk2(oa.x * silu_f(gv[0]), oa.y * silu_f(gv[1])); w.y = pk2(oa.z * silu_f(gv[2]), oa.w * silu_f(gv[3]));
;             w.z = pk2(ob.x * silu_f(gv[4]), ob.y * silu_f(gv[5])); w.w = pk2(ob.z * silu_f(gv[6]), ob.w * silu_f(gv[7]));
;             *(u32x4*)(outp + (size_t)row * DM + 8 * pc) = w; }
	v_fma_f32 v36, -v0, v35, 1.0
	v_fmac_f32_e32 v35, v36, v35
	v_div_scale_f32 v36, vcc, 1.0, v34, 1.0
	v_mul_f32_e32 v37, v36, v35
	v_fma_f32 v38, -v0, v37, v36
	v_fmac_f32_e32 v37, v38, v35
	v_fma_f32 v0, -v0, v37, v36
	v_div_fmas_f32 v0, v0, v35, v37
	v_div_fixup_f32 v0, v0, v34, 1.0
	s_nop 1
	v_mul_f32_e64 v2, v2, v0
	v_mul_f32_e64 v3, v3, v0
	v_pk_mul_f32 v[4:5], v[4:5], v[0:1] op_sel_hi:[1,0]
	v_add_u32_e32 v34, v198, v156
	ds_write_b128 v34, v[2:5] offset:40960
	v_pk_mul_f32 v[2:3], v[6:7], v[0:1] op_sel_hi:[1,0]
	v_pk_mul_f32 v[4:5], v[8:9], v[0:1] op_sel_hi:[1,0]
	ds_write_b128 v34, v[2:5] offset:40992
	v_pk_mul_f32 v[2:3], v[10:11], v[0:1] op_sel_hi:[1,0]
	v_pk_mul_f32 v[4:5], v[12:13], v[0:1] op_sel_hi:[1,0]
	ds_write_b128 v34, v[2:5] offset:41024
	v_pk_mul_f32 v[2:3], v[14:15], v[0:1] op_sel_hi:[1,0]
	v_pk_mul_f32 v[4:5], v[16:17], v[0:1] op_sel_hi:[1,0]
	ds_write_b128 v34, v[2:5] offset:41056
	v_pk_mul_f32 v[2:3], v[18:19], v[0:1] op_sel_hi:[1,0]
	v_pk_mul_f32 v[4:5], v[20:21], v[0:1] op_sel_hi:[1,0]
	ds_write_b128 v34, v[2:5] offset:41088
	v_pk_mul_f32 v[2:3], v[22:23], v[0:1] op_sel_hi:[1,0]
	v_pk_mul_f32 v[4:5], v[24:25], v[0:1] op_sel_hi:[1,0]
	ds_write_b128 v34, v[2:5] offset:41120
	v_pk_mul_f32 v[2:3], v[26:27], v[0:1] op_sel_hi:[1,0]
	v_pk_mul_f32 v[4:5], v[28:29], v[0:1] op_sel_hi:[1,0]
	ds_write_b128 v34, v[2:5] offset:41152
	v_pk_mul_f32 v[2:3], v[30:31], v[0:1] op_sel_hi:[1,0]
	v_pk_mul_f32 v[4:5], v[32:33], v[0:1] op_sel_hi:[1,0]
	ds_write_b128 v34, v[2:5] offset:41184
	v_add_u32_e32 v0, v192, v193
	ds_read_b128 v[6:9], v0 offset:40960
	ds_read_b128 v[2:5], v0 offset:40976
	s_waitcnt vmcnt(3)
	v_lshlrev_b32_e32 v14, 16, v214
	v_and_b32_e32 v15, 0xffff0000, v214
	v_mul_f32_e32 v214, 0xbfb8aa3b, v14
	v_exp_f32_e32 v214, v214
	s_nop 0
	v_add_f32_e32 v214, 1.0, v214
	v_rcp_f32_e32 v16, v214
	v_mul_f32_e32 v214, 0xbfb8aa3b, v15
	v_exp_f32_e32 v214, v214
	s_nop 0
	v_add_f32_e32 v214, 1.0, v214
	v_rcp_f32_e32 v17, v214
	v_lshlrev_b32_e32 v214, 16, v215
	v_and_b32_e32 v215, 0xffff0000, v215
	v_pk_mul_f32 v[14:15], v[16:17], v[14:15]
	s_waitcnt lgkmcnt(1)
	v_pk_mul_f32 v[6:7], v[6:7], v[14:15]
	s_nop 0
	v_cvt_pk_bf16_f32 v6, v6, v7
	v_mul_f32_e32 v7, 0xbfb8aa3b, v214
	v_exp_f32_e32 v7, v7
	s_nop 0
	v_add_f32_e32 v7, 1.0, v7
	v_rcp_f32_e32 v14, v7
	v_mul_f32_e32 v7, 0xbfb8aa3b, v215
	v_exp_f32_e32 v7, v7
	s_nop 0
	v_add_f32_e32 v7, 1.0, v7
	v_rcp_f32_e32 v15, v7
	s_nop 0
	v_pk_mul_f32 v[214:215], v[14:15], v[214:215]
	s_nop 0
	v_pk_mul_f32 v[8:9], v[8:9], v[214:215]
	s_nop 0
	v_cvt_pk_bf16_f32 v7, v8, v9
	v_lshlrev_b32_e32 v8, 16, v216
	v_and_b32_e32 v9, 0xffff0000, v216
	v_mul_f32_e32 v214, 0xbfb8aa3b, v8
	v_mul_f32_e32 v215, 0xbfb8aa3b, v9
	v_exp_f32_e32 v214, v214
	v_exp_f32_e32 v215, v215
	v_add_f32_e32 v214, 1.0, v214
	v_add_f32_e32 v215, 1.0, v215
	v_rcp_f32_e32 v214, v214
	v_rcp_f32_e32 v215, v215
	s_nop 0
	v_pk_mul_f32 v[8:9], v[214:215], v[8:9]
	s_waitcnt lgkmcnt(0)
	v_pk_mul_f32 v[2:3], v[2:3], v[8:9]
	s_nop 0
	v_cvt_pk_bf16_f32 v8, v2, v3
	v_lshlrev_b32_e32 v2, 16, v217
	v_mul_f32_e32 v9, 0xbfb8aa3b, v2
	v_exp_f32_e32 v9, v9
	v_and_b32_e32 v3, 0xffff0000, v217
	v_add_f32_e32 v9, 1.0, v9
	v_rcp_f32_e32 v214, v9
	v_mul_f32_e32 v9, 0xbfb8aa3b, v3
	v_exp_f32_e32 v9, v9
	s_nop 0
	v_add_f32_e32 v9, 1.0, v9
	v_rcp_f32_e32 v215, v9
	s_nop 0
	v_pk_mul_f32 v[2:3], v[214:215], v[2:3]
	s_nop 0
	v_pk_mul_f32 v[2:3], v[4:5], v[2:3]
	s_nop 0
	v_cvt_pk_bf16_f32 v9, v2, v3
	global_store_dwordx4 v[152:153], v[6:9], off
	ds_read_b128 v[6:9], v0 offset:43136
	ds_read_b128 v[2:5], v0 offset:43152
	s_waitcnt vmcnt(3)
	v_lshlrev_b32_e32 v14, 16, v218
	v_and_b32_e32 v15, 0xffff0000, v218
	v_mul_f32_e32 v218, 0xbfb8aa3b, v14
	v_exp_f32_e32 v218, v218
	s_nop 0
	v_add_f32_e32 v218, 1.0, v218
	v_rcp_f32_e32 v16, v218
	v_mul_f32_e32 v218, 0xbfb8aa3b, v15
	v_exp_f32_e32 v218, v218
	s_nop 0
	v_add_f32_e32 v218, 1.0, v218
	v_rcp_f32_e32 v17, v218
	v_lshlrev_b32_e32 v218, 16, v219
	v_and_b32_e32 v219, 0xffff0000, v219
	v_pk_mul_f32 v[14:15], v[16:17], v[14:15]
	s_waitcnt lgkmcnt(1)
	v_pk_mul_f32 v[6:7], v[6:7], v[14:15]
	s_nop 0
	v_cvt_pk_bf16_f32 v6, v6, v7
	v_mul_f32_e32 v7, 0xbfb8aa3b, v218
	v_exp_f32_e32 v7, v7
	s_nop 0
	v_add_f32_e32 v7, 1.0, v7
	v_rcp_f32_e32 v14, v7
	v_mul_f32_e32 v7, 0xbfb8aa3b, v219
	v_exp_f32_e32 v7, v7
	s_nop 0
	v_add_f32_e32 v7, 1.0, v7
	v_rcp_f32_e32 v15, v7
	s_nop 0
	v_pk_mul_f32 v[218:219], v[14:15], v[218:219]
	s_nop 0
	v_pk_mul_f32 v[8:9], v[8:9], v[218:219]
	s_nop 0
	v_cvt_pk_bf16_f32 v7, v8, v9
	v_lshlrev_b32_e32 v8, 16, v220
	v_and_b32_e32 v9, 0xffff0000, v220
	v_mul_f32_e32 v218, 0xbfb8aa3b, v8
	v_mul_f32_e32 v219, 0xbfb8aa3b, v9
	v_exp_f32_e32 v218, v218
	v_exp_f32_e32 v219, v219
	v_add_f32_e32 v218, 1.0, v218
	v_add_f32_e32 v219, 1.0, v219
	v_rcp_f32_e32 v218, v218
	v_rcp_f32_e32 v219, v219
	s_nop 0
	v_pk_mul_f32 v[8:9], v[218:219], v[8:9]
	s_waitcnt lgkmcnt(0)
; #define LAS __attribute__((address_space(3)))
; __device__ __forceinline__ unsigned pk2(float lo, float hi) { f32x2_t v = {lo, hi}; bf16x2_t b = __builtin_convertvector(v, bf16x2_t); return __builtin_bit_cast(unsigned, b); }
; __device__ __forceinline__ float silu_f(float v) { return v * __builtin_amdgcn_rcpf(1.0f + __expf(-v)); }
; template <bool TRACK> ...
;     ...
;         const int pc = lane & 7;
; #pragma unroll
;         for (int i = 0; i < 4; ++i) { const int rw = i * 8 + (lane >> 3), row = wave * 32 + rw;
;             const f32x4 oa = *(const LAS f32x4*)(scr + rw * 272 + pc * 32), ob = *(const LAS f32x4*)(scr + rw * 272 + pc * 32 + 16);
;             float gv[8]; unpack8(*(const u32x4*)(gate + (size_t)row * INW + 8 * pc), gv);
;             u32x4 w; w.x = pk2(oa.x * silu_f(gv[0]), oa.y * silu_f(gv[1])); w.y = pk2(oa.z * silu_f(gv[2]), oa.w * silu_f(gv[3]));
;             w.z = pk2(ob.x * silu_f(gv[4]), ob.y * silu_f(gv[5])); w.w = pk2(ob.z * silu_f(gv[6]), ob.w * silu_f(gv[7]));
;             *(u32x4*)(outp + (size_t)row * DM + 8 * pc) = w; }
	v_pk_mul_f32 v[2:3], v[2:3], v[8:9]
	s_nop 0
	v_cvt_pk_bf16_f32 v8, v2, v3
	v_lshlrev_b32_e32 v2, 16, v221
	v_mul_f32_e32 v9, 0xbfb8aa3b, v2
	v_exp_f32_e32 v9, v9
	v_and_b32_e32 v3, 0xffff0000, v221
	v_add_f32_e32 v9, 1.0, v9
	v_rcp_f32_e32 v218, v9
	v_mul_f32_e32 v9, 0xbfb8aa3b, v3
	v_exp_f32_e32 v9, v9
	s_nop 0
	v_add_f32_e32 v9, 1.0, v9
	v_rcp_f32_e32 v219, v9
	s_nop 0
	v_pk_mul_f32 v[2:3], v[218:219], v[2:3]
	s_nop 0
	v_pk_mul_f32 v[2:3], v[4:5], v[2:3]
	s_nop 0
	v_cvt_pk_bf16_f32 v9, v2, v3
	global_store_dwordx4 v[144:145], v[6:9], off
	ds_read_b128 v[6:9], v0 offset:45312
	ds_read_b128 v[2:5], v0 offset:45328
	s_waitcnt vmcnt(3)
	v_lshlrev_b32_e32 v14, 16, v222
	v_and_b32_e32 v15, 0xffff0000, v222
	v_mul_f32_e32 v222, 0xbfb8aa3b, v14
	v_exp_f32_e32 v222, v222
	s_nop 0
	v_add_f32_e32 v222, 1.0, v222
	v_rcp_f32_e32 v16, v222
	v_mul_f32_e32 v222, 0xbfb8aa3b, v15
	v_exp_f32_e32 v222, v222
	s_nop 0
	v_add_f32_e32 v222, 1.0, v222
	v_rcp_f32_e32 v17, v222
	v_lshlrev_b32_e32 v222, 16, v223
	v_and_b32_e32 v223, 0xffff0000, v223
	v_pk_mul_f32 v[14:15], v[16:17], v[14:15]
	s_waitcnt lgkmcnt(1)
	v_pk_mul_f32 v[6:7], v[6:7], v[14:15]
	s_nop 0
	v_cvt_pk_bf16_f32 v6, v6, v7
	v_mul_f32_e32 v7, 0xbfb8aa3b, v222
	v_exp_f32_e32 v7, v7
	s_nop 0
	v_add_f32_e32 v7, 1.0, v7
	v_rcp_f32_e32 v14, v7
	v_mul_f32_e32 v7, 0xbfb8aa3b, v223
	v_exp_f32_e32 v7, v7
	s_nop 0
	v_add_f32_e32 v7, 1.0, v7
	v_rcp_f32_e32 v15, v7
	s_nop 0
	v_pk_mul_f32 v[222:223], v[14:15], v[222:223]
	s_nop 0
	v_pk_mul_f32 v[8:9], v[8:9], v[222:223]
	s_nop 0
	v_cvt_pk_bf16_f32 v7, v8, v9
	v_lshlrev_b32_e32 v8, 16, v224
	v_and_b32_e32 v9, 0xffff0000, v224
	v_mul_f32_e32 v222, 0xbfb8aa3b, v8
	v_mul_f32_e32 v223, 0xbfb8aa3b, v9
	v_exp_f32_e32 v222, v222
	v_exp_f32_e32 v223, v223
	v_add_f32_e32 v222, 1.0, v222
	v_add_f32_e32 v223, 1.0, v223
	v_rcp_f32_e32 v222, v222
	v_rcp_f32_e32 v223, v223
	s_nop 0
	v_pk_mul_f32 v[8:9], v[222:223], v[8:9]
	s_waitcnt lgkmcnt(0)
	v_pk_mul_f32 v[2:3], v[2:3], v[8:9]
	s_nop 0
	v_cvt_pk_bf16_f32 v8, v2, v3
	v_lshlrev_b32_e32 v2, 16, v225
	v_mul_f32_e32 v9, 0xbfb8aa3b, v2
	v_exp_f32_e32 v9, v9
	v_and_b32_e32 v3, 0xffff0000, v225
	v_add_f32_e32 v9, 1.0, v9
	v_rcp_f32_e32 v222, v9
	v_mul_f32_e32 v9, 0xbfb8aa3b, v3
	v_exp_f32_e32 v9, v9
	s_nop 0
	v_add_f32_e32 v9, 1.0, v9
	v_rcp_f32_e32 v223, v9
	s_nop 0
	v_pk_mul_f32 v[2:3], v[222:223], v[2:3]
	s_nop 0
	v_pk_mul_f32 v[2:3], v[4:5], v[2:3]
	s_nop 0
	v_cvt_pk_bf16_f32 v9, v2, v3
	global_store_dwordx4 v[140:141], v[6:9], off
	ds_read_b128 v[6:9], v0 offset:47488
	ds_read_b128 v[2:5], v0 offset:47504
	s_waitcnt vmcnt(3)
	v_lshlrev_b32_e32 v14, 16, v226
	v_mul_f32_e32 v0, 0xbfb8aa3b, v14
	v_exp_f32_e32 v0, v0
	v_and_b32_e32 v15, 0xffff0000, v226
	v_lshlrev_b32_e32 v226, 16, v227
	v_and_b32_e32 v227, 0xffff0000, v227
	v_add_f32_e32 v0, 1.0, v0
	v_rcp_f32_e32 v16, v0
	v_mul_f32_e32 v0, 0xbfb8aa3b, v15
	v_exp_f32_e32 v0, v0
	s_nop 0
	v_add_f32_e32 v0, 1.0, v0
	v_rcp_f32_e32 v17, v0
	v_mul_f32_e32 v0, 0xbfb8aa3b, v226
	v_exp_f32_e32 v0, v0
	v_pk_mul_f32 v[14:15], v[16:17], v[14:15]
	s_waitcnt lgkmcnt(1)
	v_pk_mul_f32 v[6:7], v[6:7], v[14:15]
	v_add_f32_e32 v0, 1.0, v0
	v_rcp_f32_e32 v14, v0
	v_mul_f32_e32 v0, 0xbfb8aa3b, v227
	v_exp_f32_e32 v0, v0
	v_cvt_pk_bf16_f32 v6, v6, v7
	v_add_f32_e32 v0, 1.0, v0
	v_rcp_f32_e32 v15, v0
	s_nop 0
	v_pk_mul_f32 v[226:227], v[14:15], v[226:227]
	s_nop 0
	v_pk_mul_f32 v[8:9], v[8:9], v[226:227]
	s_nop 0
	v_cvt_pk_bf16_f32 v7, v8, v9
	v_lshlrev_b32_e32 v8, 16, v228
	v_mul_f32_e32 v0, 0xbfb8aa3b, v8
	v_exp_f32_e32 v0, v0
	v_and_b32_e32 v9, 0xffff0000, v228
	v_add_f32_e32 v0, 1.0, v0
	v_rcp_f32_e32 v226, v0
	v_mul_f32_e32 v0, 0xbfb8aa3b, v9
	v_exp_f32_e32 v0, v0
	s_nop 0
	v_add_f32_e32 v0, 1.0, v0
	v_rcp_f32_e32 v227, v0
	s_nop 0
	v_pk_mul_f32 v[8:9], v[226:227], v[8:9]
	s_waitcnt lgkmcnt(0)
	v_pk_mul_f32 v[2:3], v[2:3], v[8:9]
	s_nop 0
	v_cvt_pk_bf16_f32 v8, v2, v3
	v_lshlrev_b32_e32 v2, 16, v229
	v_mul_f32_e32 v0, 0xbfb8aa3b, v2
	v_exp_f32_e32 v0, v0
	v_and_b32_e32 v3, 0xffff0000, v229
	v_add_f32_e32 v0, 1.0, v0
	v_rcp_f32_e32 v226, v0
	v_mul_f32_e32 v0, 0xbfb8aa3b, v3
	v_exp_f32_e32 v0, v0
	s_nop 0
	v_add_f32_e32 v0, 1.0, v0
	v_rcp_f32_e32 v227, v0
	s_nop 0
	v_pk_mul_f32 v[2:3], v[226:227], v[2:3]
	s_nop 0
	v_pk_mul_f32 v[2:3], v[4:5], v[2:3]
	s_nop 0
	v_cvt_pk_bf16_f32 v9, v2, v3
	global_store_dwordx4 v[136:137], v[6:9], off
